# v15 + XCD-local release on the five GEMM-to-GEMM grid barriers (run-time guarded by a per-launch placement check, else full barrier)
# speedup vs baseline: 1.0212x; 1.0121x over previous
; #define LAS __attribute__((address_space(3)))
; __device__ __forceinline__ unsigned xb_add(unsigned* p, unsigned v) { return __hip_atomic_fetch_add(p, v, __ATOMIC_RELAXED, __HIP_MEMORY_SCOPE_AGENT); }
; __device__ __forceinline__ unsigned xb_xcc_id() { return (unsigned)__builtin_amdgcn_s_getreg((3 << 11) | 20) & 0xFu; }
; __device__ __forceinline__ XcdBarrier xcd_barrier_post(unsigned* bar, volatile LAS unsigned* st, int tid) {
;     XcdBarrier b; b.bar = bar; b.x = xb_xcc_id(); b.st = st;
;     if (tid == 0) (void)xb_add(&bar[XB_XCNT(b.x)], 1u);
;     return b;
; }
.LBB0_4:
	s_or_b64 exec, exec, s[2:3]
	s_waitcnt lgkmcnt(0)
	s_barrier
	s_getreg_b32 s1, hwreg(HW_REG_XCC_ID, 0, 4)
	s_and_saveexec_b64 s[2:3], vcc
	s_cbranch_execz .LBB0_7
	s_mov_b64 s[4:5], exec
	v_mbcnt_lo_u32_b32 v0, s4, 0
	v_mbcnt_hi_u32_b32 v0, s5, v0
	v_cmp_eq_u32_e32 vcc, 0, v0
	s_and_b64 s[6:7], exec, vcc
	s_mov_b64 exec, s[6:7]
	s_cbranch_execz .LBB0_7
	s_and_b32 s6, s33, 7
	s_lshl_b32 s6, s6, 8
	s_and_b32 s7, s1, 15
	s_lshl_b32 s7, 1, s7
	v_mov_b32_e32 v2, s6
	v_mov_b32_e32 v3, s7
	global_atomic_or v2, v3, s[40:41] offset:1028
	s_waitcnt vmcnt(0)
	s_lshl_b32 s1, s1, 8
	s_and_b32 s1, s1, 0xf00
	s_bcnt1_i32_b64 s4, s[4:5]
	v_mov_b32_e32 v0, s1
	v_mov_b32_e32 v1, s4
	global_atomic_add v0, v1, s[40:41] offset:1024

; __device__ __forceinline__ unsigned xb_ld(unsigned* p)              { return __hip_atomic_load(p, __ATOMIC_RELAXED, __HIP_MEMORY_SCOPE_AGENT); }
; __device__ __forceinline__ unsigned xb_add(unsigned* p, unsigned v) { return __hip_atomic_fetch_add(p, v, __ATOMIC_RELAXED, __HIP_MEMORY_SCOPE_AGENT); }
; __device__ __forceinline__ void xcd_barrier_complete(unsigned* bar, unsigned x, unsigned& nloc, unsigned& nx) {
;     const unsigned G = gridDim.x;
;     unsigned sum, cnt, mine, sp = 0u;
;     for (;;) {
;         sum = 0u; cnt = 0u; mine = 0u;
; #pragma unroll
;         for (unsigned j = 0; j < 16; ++j) { const unsigned c = xb_ld(&bar[XB_XCNT(j)]); sum += c; cnt += (c > 0u) ? 1u : 0u; mine = (j == x) ? c : mine; }
;         if (sum == G) break;
;         __builtin_amdgcn_s_sleep(1);
;         if ((++sp & 255u) == 0u) { if (xb_ld(&bar[XB_TMO])) break; if (sp > XB_SPIN_CAP) { atomicAdd(&bar[XB_TMO], 1u); break; } }
;     }
;     nloc = mine > 0u ? mine : 1u; nx = cnt > 0u ? cnt : 1u;
; }
; __device__ __forceinline__ void xcd_barrier(const XcdBarrier& b, int tid) {
;     asm volatile("s_waitcnt vmcnt(0)" ::: "memory");
;     __syncthreads();
;     if (tid == 0) {
;         unsigned* bar = b.bar;
;         __builtin_amdgcn_s_waitcnt(0);
;         unsigned nloc = b.st[0], nx = b.st[1];
;         if (nloc == 0u) { xcd_barrier_complete(bar, b.x, nloc, nx); b.st[0] = nloc; b.st[1] = nx; }
;         const unsigned old = xb_add(&bar[XB_XSUB(b.x)], 1u);
;         const unsigned gen = old / nloc;
;         if (old + 1u == (gen + 1u) * nloc) {
;             __builtin_amdgcn_fence(__ATOMIC_RELEASE, "agent");
;             asm volatile("s_waitcnt vmcnt(0)" ::: "memory");
;             const unsigned og = xb_add(&bar[XB_TOP], 1u);
;             const unsigned tg = og / nx;
;             if (og + 1u == (tg + 1u) * nx) xb_add(&bar[XB_TOPGEN], 1u);
;             else XB_SPIN(xb_ld(&bar[XB_TOPGEN]) == tg, bar);
;             __builtin_amdgcn_fence(__ATOMIC_ACQUIRE, "agent");
;             xb_add(&bar[XB_XGEN(b.x)], 1u);
;             asm volatile("s_waitcnt vmcnt(0)" ::: "memory");
;         } else {
;             XB_SPIN(xb_ld(&bar[XB_XGEN(b.x)]) == gen, bar);
.LBB0_331:
	s_or_b64 exec, exec, s[10:11]
	v_mov_b32_e32 v14, 0
	global_load_dword v6, v14, s[40:41] offset:1028 sc1
	global_load_dword v7, v14, s[40:41] offset:1284 sc1
	global_load_dword v8, v14, s[40:41] offset:1540 sc1
	global_load_dword v9, v14, s[40:41] offset:1796 sc1
	global_load_dword v10, v14, s[40:41] offset:2052 sc1
	global_load_dword v11, v14, s[40:41] offset:2308 sc1
	global_load_dword v12, v14, s[40:41] offset:2564 sc1
	global_load_dword v13, v14, s[40:41] offset:2820 sc1
	v_cvt_f32_u32_e32 v4, v2
	s_waitcnt vmcnt(0)
	v_readfirstlane_b32 s0, v3
	s_mov_b32 s12, 1
	s_and_b32 s1, s66, 7
	s_cmp_eq_u32 s1, 0
	s_cselect_b32 s12, s12, 0
	v_readfirstlane_b32 s1, v6
	s_bcnt1_i32_b32 s1, s1
	s_cmp_eq_u32 s1, 1
	s_cselect_b32 s12, s12, 0
	v_readfirstlane_b32 s1, v7
	s_bcnt1_i32_b32 s1, s1
	s_cmp_eq_u32 s1, 1
	s_cselect_b32 s12, s12, 0
	v_readfirstlane_b32 s1, v8
	s_bcnt1_i32_b32 s1, s1
	s_cmp_eq_u32 s1, 1
	s_cselect_b32 s12, s12, 0
	v_readfirstlane_b32 s1, v9
	s_bcnt1_i32_b32 s1, s1
	s_cmp_eq_u32 s1, 1
	s_cselect_b32 s12, s12, 0
	v_readfirstlane_b32 s1, v10
	s_bcnt1_i32_b32 s1, s1
	s_cmp_eq_u32 s1, 1
	s_cselect_b32 s12, s12, 0
	v_readfirstlane_b32 s1, v11
	s_bcnt1_i32_b32 s1, s1
	s_cmp_eq_u32 s1, 1
	s_cselect_b32 s12, s12, 0
	v_readfirstlane_b32 s1, v12
	s_bcnt1_i32_b32 s1, s1
	s_cmp_eq_u32 s1, 1
	s_cselect_b32 s12, s12, 0
	v_readfirstlane_b32 s1, v13
	s_bcnt1_i32_b32 s1, s1
	s_cmp_eq_u32 s1, 1
	s_cselect_b32 s12, s12, 0
	v_writelane_b32 v248, s12, 32
	v_sub_u32_e32 v3, 0, v2
	v_rcp_iflag_f32_e32 v4, v4
	v_add_u32_e32 v5, s0, v1
	v_mul_f32_e32 v4, 0x4f7ffffe, v4
	v_cvt_u32_f32_e32 v4, v4
	v_mul_lo_u32 v1, v3, v4
	v_mul_hi_u32 v1, v4, v1
	v_add_u32_e32 v1, v4, v1
	v_mul_hi_u32 v1, v5, v1
	v_mul_lo_u32 v3, v1, v2
	v_sub_u32_e32 v3, v5, v3
	v_add_u32_e32 v4, 1, v1
	v_cmp_ge_u32_e32 vcc, v3, v2
	s_nop 1
	v_cndmask_b32_e32 v1, v1, v4, vcc
	v_sub_u32_e32 v4, v3, v2
	v_cndmask_b32_e32 v3, v3, v4, vcc
	v_add_u32_e32 v4, 1, v1
	v_cmp_ge_u32_e32 vcc, v3, v2
	v_add_u32_e32 v3, 1, v5
	s_nop 0
	v_cndmask_b32_e32 v1, v1, v4, vcc
	v_mul_lo_u32 v4, v2, v1
	v_add_u32_e32 v2, v4, v2
	v_cmp_ne_u32_e32 vcc, v3, v2
	s_and_saveexec_b64 s[0:1], vcc
	s_xor_b64 s[8:9], exec, s[0:1]
	s_cbranch_execz .LBB0_345
	s_waitcnt lgkmcnt(0)
	v_mov_b32_e32 v0, 0x2000
	global_load_dword v0, v0, s[6:7] offset:1024 sc1
	s_add_u32 s12, s6, 0x2400
	s_addc_u32 s13, s7, 0
	s_waitcnt vmcnt(0)
	v_cmp_eq_u32_e32 vcc, v0, v1
	s_and_saveexec_b64 s[10:11], vcc
	s_cbranch_execz .LBB0_344
	s_mov_b32 s0, 1
	s_mov_b64 s[14:15], 0
	v_mov_b32_e32 v0, 0
	s_branch .LBB0_335

; __device__ __forceinline__ unsigned xb_ld(unsigned* p)              { return __hip_atomic_load(p, __ATOMIC_RELAXED, __HIP_MEMORY_SCOPE_AGENT); }
; __device__ __forceinline__ unsigned xb_add(unsigned* p, unsigned v) { return __hip_atomic_fetch_add(p, v, __ATOMIC_RELAXED, __HIP_MEMORY_SCOPE_AGENT); }
; #define XB_SPIN(cond, bar) do { unsigned _sp = 0; while (cond) { __builtin_amdgcn_s_sleep(1); \
;     if ((++_sp & 255u) == 0u) { if (xb_ld(&(bar)[XB_TMO])) break; if (_sp > XB_SPIN_CAP) { atomicAdd(&(bar)[XB_TMO], 1u); break; } } } } while (0)
; __device__ __forceinline__ void xcd_barrier(const XcdBarrier& b, int tid) {
;     ...
;         const unsigned old = xb_add(&bar[XB_XSUB(b.x)], 1u);
;         const unsigned gen = old / nloc;
;         if (old + 1u == (gen + 1u) * nloc) {
;             __builtin_amdgcn_fence(__ATOMIC_RELEASE, "agent");
;             asm volatile("s_waitcnt vmcnt(0)" ::: "memory");
;             const unsigned og = xb_add(&bar[XB_TOP], 1u);
;             const unsigned tg = og / nx;
;             if (og + 1u == (tg + 1u) * nx) xb_add(&bar[XB_TOPGEN], 1u);
;             else XB_SPIN(xb_ld(&bar[XB_TOPGEN]) == tg, bar);
;             __builtin_amdgcn_fence(__ATOMIC_ACQUIRE, "agent");
;             xb_add(&bar[XB_XGEN(b.x)], 1u);
.LBB0_416:
	s_andn2_saveexec_b64 s[0:1], s[8:9]
	s_cbranch_execz .LBB0_436
	s_mov_b64 s[8:9], exec
	v_readlane_b32 s0, v248, 32
	s_nop 3
	s_cmp_eq_u32 s0, 1
	s_cbranch_scc1 .LBB0_433
	buffer_wbl2 sc1
	s_waitcnt lgkmcnt(0)
	s_waitcnt vmcnt(0)
	v_mbcnt_lo_u32_b32 v1, s8, 0
	v_mbcnt_hi_u32_b32 v1, s9, v1
	v_cmp_eq_u32_e32 vcc, 0, v1
	s_and_saveexec_b64 s[10:11], vcc
	s_cbranch_execz .LBB0_419
	s_bcnt1_i32_b64 s0, s[8:9]
	v_mov_b32_e32 v2, 0x3000
	v_mov_b32_e32 v3, s0
	global_atomic_add v2, v2, v3, s[40:41] offset:1024 sc0
